# NSA fast paths (hand-scheduled QK+softmax+PV for fully visible tiles), tile-list prefetch, woven general path, nt proj stores
# speedup vs baseline: 1.5009x; 1.0245x over previous
; #define LAS __attribute__((address_space(3)))
; DI void co_issue(const Params& P, LAS unsigned char* ring, int slot, unsigned desc, int b, int g, int wave, int lane) {
;     const int mode = (int)(desc >> 16), key_base = (int)(desc & 0xffffu);
;     const bf16_t* kb; const bf16_t* vb; unsigned ks_b, vs_b;
;     if (mode <= 1) { kb = P_kc + (size_t)(b * 2 + g) * 128 * 128; ks_b = 256u; vb = P_vcT + (size_t)(b * 2 + g) * 128 * 128; vs_b = 256u; }
;     else if (mode == 2) { kb = P_proj + (size_t)b * TT * LDP + C_KWIN + g * 128; ks_b = LDP * 2u; vb = P_vwinT + (size_t)(b * 2 + g) * 128 * TT; vs_b = TT * 2u; }
;     else { kb = P_proj + (size_t)b * TT * LDP + C_KSLC + g * 128; ks_b = LDP * 2u; vb = P_vslcT + (size_t)(b * 2 + g) * 128 * TT; vs_b = TT * 2u; }
.LBB0_508:
	v_mov_b32_e32 v239, s69
	ds_read_b32 v238, v239
	s_andn2_b64 vcc, exec, s[2:3]
	s_cbranch_vccnz .LBB0_510
	s_waitcnt vmcnt(2)
.LBB0_510:
	s_waitcnt lgkmcnt(0)
	s_barrier
	s_cmp_gt_i32 s77, s33
	s_cbranch_scc1 .LBB0_515
	v_cmp_gt_u32_e32 vcc, s46, v238
	v_readfirstlane_b32 s81, v238
	s_cbranch_vccnz .LBB0_513
	s_cmp_lt_u32 s81, 0x30000
	s_cselect_b32 s0, 0x4000, s51
	s_cselect_b32 s16, s50, 0x3c800000
	s_add_u32 s2, s73, s0
	s_addc_u32 s3, s74, 0
	s_movk_i32 s82, 0x7600
	s_movk_i32 s80, 0x1000
	s_mov_b64 s[8:9], s[16:17]
	s_mov_b64 s[40:41], s[20:21]
	s_branch .LBB0_514

; #define LAS __attribute__((address_space(3)))
; template <int MODE>
; DI void co_finish(f32x16 S, LAS unsigned char* st, int key_base, AttnState& as, int tq, bool rowsel, int vb_in, int hh) {
;     const int vb = vb_in;
;     {
;         const int base = key_base + 4 * hh;
;         const int hi = (MODE == 0) ? (((tq - 31) >> 4) - base) : (tq - base);
;         const int lo = hi - 512;
; #pragma unroll
;         for (int i = 0; i < 16; ++i) { const int c = (i & 3) + 8 * (i >> 2); bool ok = (c <= hi); if (MODE == 2) ok = ok && (c > lo); if (MODE == 1) ok = ok && rowsel; S[i] = ok ? S[i] : -1e30f; }
;     }
.LBB0_515:
	s_add_i32 s0, s68, 31
	s_cmp_ge_i32 s0, s71
	s_cselect_b64 s[0:1], -1, 0
	s_cmp_le_i32 s68, s72
	s_cselect_b64 s[2:3], -1, 0
	s_and_b64 s[8:9], s[0:1], s[2:3]
	s_and_b32 s16, s76, 0xc000
	v_cndmask_b32_e64 v0, 0, 1, s[8:9]
	v_cmp_ne_u32_e64 s[2:3], 1, v0
	s_andn2_b64 vcc, exec, s[8:9]
	s_add_i32 s16, s16, 0
	s_cbranch_vccnz .LBB0_517
	s_andn2_b64 vcc, exec, s[36:37]
	s_cbranch_vccnz .Lfast_win_orig
	s_add_i32 s88, s72, s79
	s_sub_i32 s88, s88, 34
	s_cmp_lt_u32 s88, 0x1de
	s_cbranch_scc1 .Lfast_win
	s_branch .Lfs_win
.Lfast_win_orig:
	s_setprio 1
	v_add_u32_e32 v0, s16, v162
	ds_read_b128 v[2:5], v0
	v_add_u32_e32 v0, s16, v164
	ds_read_b128 v[6:9], v0
	v_add_u32_e32 v0, s16, v165
	s_waitcnt lgkmcnt(0)
	v_mfma_f32_32x32x16_bf16 v[96:111], v[2:5], v[112:115], 0
	ds_read_b128 v[2:5], v0
	v_add_u32_e32 v0, s16, v166
	v_mfma_f32_32x32x16_bf16 v[96:111], v[6:9], v[116:119], v[96:111]
	ds_read_b128 v[6:9], v0
	v_add_u32_e32 v0, s16, v167
	s_waitcnt lgkmcnt(0)
	v_mfma_f32_32x32x16_bf16 v[96:111], v[2:5], v[120:123], v[96:111]
	ds_read_b128 v[2:5], v0
	v_add_u32_e32 v0, s16, v168
	v_mfma_f32_32x32x16_bf16 v[96:111], v[6:9], v[124:127], v[96:111]
	ds_read_b128 v[6:9], v0
	v_add_u32_e32 v0, s16, v169
	s_waitcnt lgkmcnt(0)
	v_mfma_f32_32x32x16_bf16 v[96:111], v[2:5], v[128:131], v[96:111]
	ds_read_b128 v[2:5], v0
	v_add_u32_e32 v0, s16, v170
	v_mfma_f32_32x32x16_bf16 v[96:111], v[6:9], v[132:135], v[96:111]
	ds_read_b128 v[6:9], v0
	s_waitcnt lgkmcnt(0)
	v_mfma_f32_32x32x16_bf16 v[96:111], v[2:5], v[136:139], v[96:111]
	v_mfma_f32_32x32x16_bf16 v[96:111], v[6:9], v[140:143], v[96:111]
	s_setprio 0
; #define LAS __attribute__((address_space(3)))
; DI float xh_max(float x) { const unsigned u = __float_as_uint(x); const auto r = __builtin_amdgcn_permlane32_swap(u, u, false, false); return fmaxf(__uint_as_float(r[0]), __uint_as_float(r[1])); }
; DI float xh_sum(float x) { const unsigned u = __float_as_uint(x); const auto r = __builtin_amdgcn_permlane32_swap(u, u, false, false); return __uint_as_float(r[0]) + __uint_as_float(r[1]); }
; template <int MODE>
; DI void co_finish(f32x16 S, LAS unsigned char* st, int key_base, AttnState& as, int tq, bool rowsel, int vb_in, int hh) {
;     const int vb = vb_in;
;     {
;         const int base = key_base + 4 * hh;
;         const int hi = (MODE == 0) ? (((tq - 31) >> 4) - base) : (tq - base);
;         const int lo = hi - 512;
; #pragma unroll
;         for (int i = 0; i < 16; ++i) { const int c = (i & 3) + 8 * (i >> 2); bool ok = (c <= hi); if (MODE == 2) ok = ok && (c > lo); if (MODE == 1) ok = ok && rowsel; S[i] = ok ? S[i] : -1e30f; }
;     }
;     float mx = S[0];
; #pragma unroll
;     for (int i = 1; i < 16; ++i) mx = fmaxf(mx, S[i]);
;     mx = xh_max(mx);
;     const float mxs = mx * SM_SCALE; const bool need = mxs > as.m + 8.f;
;     const float mnew = need ? mxs : as.m, muse = -fmaxf(mnew, -1e20f); float ps = 0.f;
; #pragma unroll
;     for (int i = 0; i < 16; ++i) { const float p = __builtin_amdgcn_exp2f(__builtin_fmaf(S[i], SM_SCALE, muse)); S[i] = p; ps += p; }
;     ps = xh_sum(ps);
;     if (__builtin_amdgcn_ballot_w64(need) != 0ull) {
;         const float alpha = __builtin_amdgcn_exp2f(as.m - mnew);
;         as.l *= alpha;
; #pragma unroll
;         for (int dt = 0; dt < 4; ++dt)
; #pragma unroll
;             for (int i = 0; i < 16; ++i) as.acc[dt][i] *= alpha;
;     }
.LBB0_517:
	s_andn2_b64 vcc, exec, s[36:37]
	s_cbranch_vccnz .LBB0_521
	s_add_i32 s88, s72, s79
	s_sub_i32 s88, s88, 34
	s_cmp_lt_u32 s88, 0x1de
	s_cbranch_scc1 .Lfastf_win
	v_add_u32_e32 v0, s79, v145
	v_cmp_gt_u32_e32 vcc, s53, v0
	v_add_u32_e32 v3, -1, v0
	v_add_u32_e32 v4, -2, v0
	v_cndmask_b32_e32 v2, v153, v16, vcc
	v_cmp_gt_u32_e32 vcc, s53, v3
	v_add_u32_e32 v5, -3, v0
	v_add_u32_e32 v6, -8, v0
	v_cndmask_b32_e32 v3, v153, v17, vcc
	v_cmp_gt_u32_e32 vcc, s53, v4
	v_add_u32_e32 v7, -9, v0
	v_add_u32_e32 v8, -10, v0
	v_cndmask_b32_e32 v4, v153, v18, vcc
	v_cmp_gt_u32_e32 vcc, s53, v5
	v_add_u32_e32 v9, -11, v0
	v_add_u32_e32 v10, -16, v0
	v_cndmask_b32_e32 v5, v153, v19, vcc
	v_cmp_gt_u32_e32 vcc, s53, v6
	v_subrev_u32_e32 v11, 17, v0
	v_subrev_u32_e32 v12, 18, v0
	v_cndmask_b32_e32 v6, v153, v20, vcc
	v_cmp_gt_u32_e32 vcc, s53, v7
	v_subrev_u32_e32 v13, 19, v0
	v_subrev_u32_e32 v14, 24, v0
	v_cndmask_b32_e32 v7, v153, v21, vcc
	v_cmp_gt_u32_e32 vcc, s53, v8
	v_subrev_u32_e32 v15, 25, v0
	v_subrev_u32_e32 v176, 26, v0
	v_cndmask_b32_e32 v8, v153, v22, vcc
	v_cmp_gt_u32_e32 vcc, s53, v9
	v_subrev_u32_e32 v0, 27, v0
	s_nop 0
	v_cndmask_b32_e32 v9, v153, v23, vcc
	v_cmp_gt_u32_e32 vcc, s53, v10
	s_nop 1
	v_cndmask_b32_e32 v10, v153, v24, vcc
	v_cmp_gt_u32_e32 vcc, s53, v11
	s_nop 1
	v_cndmask_b32_e32 v11, v153, v25, vcc
	v_cmp_gt_u32_e32 vcc, s53, v12
	s_nop 1
	v_cndmask_b32_e32 v12, v153, v26, vcc
	v_cmp_gt_u32_e32 vcc, s53, v13
	s_nop 1
	v_cndmask_b32_e32 v13, v153, v27, vcc
	v_cmp_gt_u32_e32 vcc, s53, v14
	s_nop 1
	v_cndmask_b32_e32 v14, v153, v28, vcc
	v_cmp_gt_u32_e32 vcc, s53, v15
	s_nop 1
	v_cndmask_b32_e32 v15, v153, v29, vcc
	v_cmp_gt_u32_e32 vcc, s53, v176
	v_max_f32_e32 v176, v3, v3
	s_nop 0
	v_cndmask_b32_e32 v178, v153, v30, vcc
	v_cmp_gt_u32_e32 vcc, s53, v0
	v_max_f32_e32 v0, v2, v2
	v_max_f32_e32 v0, v0, v176
	v_max3_f32 v0, v0, v4, v5
	v_max3_f32 v0, v0, v6, v7
	v_max3_f32 v0, v0, v8, v9
	v_max3_f32 v0, v0, v10, v11
	v_max3_f32 v0, v0, v12, v13
	v_cndmask_b32_e32 v179, v153, v31, vcc
	v_max3_f32 v0, v0, v14, v15
	v_max3_f32 v0, v0, v178, v179
	v_mov_b32_e32 v176, v0
	s_nop 1
	v_permlane32_swap_b32_e32 v0, v176
	v_max_f32_e32 v176, v176, v176
	v_max_f32_e32 v0, v0, v0
	v_max_f32_e32 v0, v0, v176
	v_mul_f32_e32 v0, 0x3e0293ee, v0
	v_add_f32_e32 v176, 0x41000000, v177
	v_cmp_gt_f32_e32 vcc, v0, v176
	s_nop 1
	v_cndmask_b32_e32 v176, v177, v0, vcc
	v_max_f32_e32 v0, v176, v176
	v_max_f32_e32 v180, 0xe0ad78ec, v0
	v_fma_f32 v0, v2, s52, -v180
	v_exp_f32_e32 v0, v0
	v_fma_f32 v2, v3, s52, -v180
	v_exp_f32_e32 v2, v2
	v_fma_f32 v3, v4, s52, -v180
	v_exp_f32_e32 v3, v3
	v_fma_f32 v4, v5, s52, -v180
	v_exp_f32_e32 v4, v4
	v_add_f32_e32 v5, 0, v0
	v_add_f32_e32 v5, v2, v5
	v_add_f32_e32 v5, v3, v5
	v_add_f32_e32 v181, v4, v5
	v_fma_f32 v5, v6, s52, -v180
	v_exp_f32_e32 v5, v5
	v_fma_f32 v6, v7, s52, -v180
	v_exp_f32_e32 v6, v6
	v_fma_f32 v7, v8, s52, -v180
	v_exp_f32_e32 v7, v7
	v_fma_f32 v8, v9, s52, -v180
	v_exp_f32_e32 v8, v8
	v_add_f32_e32 v9, v5, v181
	v_add_f32_e32 v9, v6, v9
	v_add_f32_e32 v9, v7, v9
	v_add_f32_e32 v181, v8, v9
	v_fma_f32 v9, v10, s52, -v180
	v_exp_f32_e32 v9, v9
	v_fma_f32 v10, v11, s52, -v180
	v_exp_f32_e32 v10, v10
	v_fma_f32 v11, v12, s52, -v180
	v_exp_f32_e32 v11, v11
	v_fma_f32 v12, v13, s52, -v180
	v_exp_f32_e32 v12, v12
	v_add_f32_e32 v13, v9, v181
	v_add_f32_e32 v13, v10, v13
	v_add_f32_e32 v13, v11, v13
	v_add_f32_e32 v181, v12, v13
	v_fma_f32 v13, v14, s52, -v180
	v_exp_f32_e32 v13, v13
	v_fma_f32 v14, v15, s52, -v180
	v_exp_f32_e32 v14, v14
	v_fma_f32 v15, v178, s52, -v180
	v_exp_f32_e32 v15, v15
	v_fma_f32 v178, v179, s52, -v180
	v_exp_f32_e32 v178, v178
	v_add_f32_e32 v179, v13, v181
	v_add_f32_e32 v179, v14, v179
	v_add_f32_e32 v179, v15, v179
	v_add_f32_e32 v179, v178, v179
	v_mov_b32_e32 v180, v179
	s_nop 1
	v_permlane32_swap_b32_e32 v179, v180
	s_cbranch_vccz .LBB0_520
	v_sub_f32_e32 v177, v177, v176
	v_exp_f32_e32 v182, v177
	s_nop 0
	v_mul_f32_e32 v175, v175, v182
	v_pk_mul_f32 v[94:95], v[94:95], v[182:183] op_sel_hi:[1,0]
	v_pk_mul_f32 v[92:93], v[92:93], v[182:183] op_sel_hi:[1,0]
	v_pk_mul_f32 v[90:91], v[90:91], v[182:183] op_sel_hi:[1,0]
	v_pk_mul_f32 v[88:89], v[88:89], v[182:183] op_sel_hi:[1,0]
	v_pk_mul_f32 v[86:87], v[86:87], v[182:183] op_sel_hi:[1,0]
	v_pk_mul_f32 v[84:85], v[84:85], v[182:183] op_sel_hi:[1,0]
	v_pk_mul_f32 v[82:83], v[82:83], v[182:183] op_sel_hi:[1,0]
	v_pk_mul_f32 v[80:81], v[80:81], v[182:183] op_sel_hi:[1,0]
	v_pk_mul_f32 v[78:79], v[78:79], v[182:183] op_sel_hi:[1,0]
	v_pk_mul_f32 v[76:77], v[76:77], v[182:183] op_sel_hi:[1,0]
	v_pk_mul_f32 v[74:75], v[74:75], v[182:183] op_sel_hi:[1,0]
	v_pk_mul_f32 v[72:73], v[72:73], v[182:183] op_sel_hi:[1,0]
	v_pk_mul_f32 v[70:71], v[70:71], v[182:183] op_sel_hi:[1,0]
	v_pk_mul_f32 v[68:69], v[68:69], v[182:183] op_sel_hi:[1,0]
	v_pk_mul_f32 v[66:67], v[66:67], v[182:183] op_sel_hi:[1,0]
	v_pk_mul_f32 v[64:65], v[64:65], v[182:183] op_sel_hi:[1,0]
	v_pk_mul_f32 v[62:63], v[62:63], v[182:183] op_sel_hi:[1,0]
	v_pk_mul_f32 v[60:61], v[60:61], v[182:183] op_sel_hi:[1,0]
	v_pk_mul_f32 v[58:59], v[58:59], v[182:183] op_sel_hi:[1,0]
	v_pk_mul_f32 v[56:57], v[56:57], v[182:183] op_sel_hi:[1,0]
	v_pk_mul_f32 v[54:55], v[54:55], v[182:183] op_sel_hi:[1,0]
	v_pk_mul_f32 v[52:53], v[52:53], v[182:183] op_sel_hi:[1,0]
	v_pk_mul_f32 v[50:51], v[50:51], v[182:183] op_sel_hi:[1,0]
	v_pk_mul_f32 v[48:49], v[48:49], v[182:183] op_sel_hi:[1,0]
	v_pk_mul_f32 v[46:47], v[46:47], v[182:183] op_sel_hi:[1,0]
	v_pk_mul_f32 v[44:45], v[44:45], v[182:183] op_sel_hi:[1,0]
	v_pk_mul_f32 v[42:43], v[42:43], v[182:183] op_sel_hi:[1,0]
	v_pk_mul_f32 v[40:41], v[40:41], v[182:183] op_sel_hi:[1,0]
	v_pk_mul_f32 v[38:39], v[38:39], v[182:183] op_sel_hi:[1,0]
	v_pk_mul_f32 v[36:37], v[36:37], v[182:183] op_sel_hi:[1,0]
	v_pk_mul_f32 v[34:35], v[34:35], v[182:183] op_sel_hi:[1,0]
	v_pk_mul_f32 v[32:33], v[32:33], v[182:183] op_sel_hi:[1,0]

; #define CO_STEP2(list, n, i) do { \
;     if ((n) - 1 - (i) >= 1) asm volatile("s_waitcnt vmcnt(2)" ::: "memory"); else asm volatile("s_waitcnt vmcnt(0)" ::: "memory"); \
;     asm volatile("s_waitcnt lgkmcnt(0)" ::: "memory"); __builtin_amdgcn_s_barrier(); asm volatile("" ::: "memory"); \
;     if ((i) + 2 < (n)) co_issue(P, ring, ((i) + 2) & 3, (list)[(i) + 2], b, g, wave, lane); } while (0)
; #define CO_PIPE(MODE, REL, KB, RS) do { const bool rel_ = (REL); LAS unsigned char* sp_ = ring + (i & 3) * 16384; f32x16 Sn_; \
;     if (rel_) Sn_ = co_qk1(sp_, qf, ka); \
;     if (pend) co_finish<MODE>(Sp, pst, pkb, st, tq, prs, vb, hh); \
;     pend = rel_; if (rel_) { Sp = Sn_; pst = sp_; pkb = (KB); prs = (RS); } } while (0)
; DI void nsa_block_item(const Params& P, unsigned char* smem_g, int b, int g, int tb, int tid_in) {
;     ...
;     for (i = 0; i < n2; ++i) {
;         CO_STEP2(list2, n2, i); const int kb_ = (int)(list2[i] & 0xffffu); const int j = kb_ >> 6;
;         CO_PIPE(1, ((Uw >> j) & 1u) && kb_ <= t0 + 3, kb_, (bool)((mysel >> j) & 1u));
.LBB0_541:
	s_waitcnt lgkmcnt(0)
	s_barrier
	s_cmp_lg_u32 s41, 0
	s_cbranch_scc1 .Lsel_pf_ok
	v_mov_b32_e32 v239, s71
	ds_read_b32 v238, v239 offset:8
	ds_read_b32 v237, v239
	s_waitcnt lgkmcnt(0)
.Lsel_pf_ok:
	s_add_i32 s73, s41, 2
	s_cmp_ge_i32 s73, s33
	s_cbranch_scc1 .LBB0_546
	v_cmp_gt_u32_e32 vcc, s46, v238
	v_readfirstlane_b32 s76, v238
	s_cbranch_vccnz .LBB0_544
	s_cmp_lt_u32 s76, 0x30000
	s_cselect_b32 s16, s50, 0x3c800000
	s_cselect_b32 s3, s69, s66
	s_cselect_b32 s2, s68, s63
	s_movk_i32 s77, 0x7600
	s_movk_i32 s75, 0x1000
	s_mov_b64 s[8:9], s[16:17]
	s_mov_b64 s[40:41], s[20:21]
	s_branch .LBB0_545

; #define LAS __attribute__((address_space(3)))
; #define CO_STEP2(list, n, i) do { \
;     if ((n) - 1 - (i) >= 1) asm volatile("s_waitcnt vmcnt(2)" ::: "memory"); else asm volatile("s_waitcnt vmcnt(0)" ::: "memory"); \
;     asm volatile("s_waitcnt lgkmcnt(0)" ::: "memory"); __builtin_amdgcn_s_barrier(); asm volatile("" ::: "memory"); \
;     if ((i) + 2 < (n)) co_issue(P, ring, ((i) + 2) & 3, (list)[(i) + 2], b, g, wave, lane); } while (0)
; #define CO_PIPE(MODE, REL, KB, RS) do { const bool rel_ = (REL); LAS unsigned char* sp_ = ring + (i & 3) * 16384; f32x16 Sn_; \
;     if (rel_) Sn_ = co_qk1(sp_, qf, ka); \
;     if (pend) co_finish<MODE>(Sp, pst, pkb, st, tq, prs, vb, hh); \
;     pend = rel_; if (rel_) { Sp = Sn_; pst = sp_; pkb = (KB); prs = (RS); } } while (0)
; template <int MODE>
; DI void co_finish(f32x16 S, LAS unsigned char* st, int key_base, AttnState& as, int tq, bool rowsel, int vb_in, int hh) {
;     const int vb = vb_in;
;     {
;         const int base = key_base + 4 * hh;
;         const int hi = (MODE == 0) ? (((tq - 31) >> 4) - base) : (tq - base);
;         const int lo = hi - 512;
; #pragma unroll
;         for (int i = 0; i < 16; ++i) { const int c = (i & 3) + 8 * (i >> 2); bool ok = (c <= hi); if (MODE == 2) ok = ok && (c > lo); if (MODE == 1) ok = ok && rowsel; S[i] = ok ? S[i] : -1e30f; }
;     }
; DI void nsa_block_item(const Params& P, unsigned char* smem_g, int b, int g, int tb, int tid_in) {
;     ...
;         CO_STEP2(list2, n2, i); const int kb_ = (int)(list2[i] & 0xffffu); const int j = kb_ >> 6;
;         CO_PIPE(1, ((Uw >> j) & 1u) && kb_ <= t0 + 3, kb_, (bool)((mysel >> j) & 1u));
.LBB0_546:
	v_readfirstlane_b32 s0, v237
	s_and_b32 s16, s0, 0xffff
	s_bfe_u32 s0, s0, 0xa0006
	s_lshl_b32 s41, 1, s0
	s_and_b32 s0, s41, s70
	s_cmp_lg_u32 s0, 0
	s_cselect_b64 s[0:1], -1, 0
	s_cmp_le_i32 s16, s25
	s_cselect_b64 s[2:3], -1, 0
	s_and_b64 s[8:9], s[0:1], s[2:3]
	s_and_b32 s40, s72, 0xc000
	v_cndmask_b32_e64 v0, 0, 1, s[8:9]
	v_cmp_ne_u32_e64 s[2:3], 1, v0
	s_andn2_b64 vcc, exec, s[8:9]
	s_add_i32 s40, s40, 0
	s_cbranch_vccnz .LBB0_548
	s_andn2_b64 vcc, exec, s[36:37]
	s_cbranch_vccnz .Lfast_sel_orig
	s_add_i32 s88, s59, s74
	s_cmp_ge_i32 s88, 31
	s_cbranch_scc1 .Lfast_sel
	s_branch .Lfs_sel
.Lfast_sel_orig:
	s_setprio 1
	v_add_u32_e32 v0, s40, v162
	ds_read_b128 v[2:5], v0
	v_add_u32_e32 v0, s40, v164
	ds_read_b128 v[6:9], v0
	v_add_u32_e32 v0, s40, v165
	s_waitcnt lgkmcnt(0)
	v_mfma_f32_32x32x16_bf16 v[96:111], v[2:5], v[112:115], 0
	ds_read_b128 v[2:5], v0
	v_add_u32_e32 v0, s40, v166
	v_mfma_f32_32x32x16_bf16 v[96:111], v[6:9], v[116:119], v[96:111]
	ds_read_b128 v[6:9], v0
	v_add_u32_e32 v0, s40, v167
	s_waitcnt lgkmcnt(0)
	v_mfma_f32_32x32x16_bf16 v[96:111], v[2:5], v[120:123], v[96:111]
	ds_read_b128 v[2:5], v0
	v_add_u32_e32 v0, s40, v168
	v_mfma_f32_32x32x16_bf16 v[96:111], v[6:9], v[124:127], v[96:111]
	ds_read_b128 v[6:9], v0
	v_add_u32_e32 v0, s40, v169
	s_waitcnt lgkmcnt(0)
	v_mfma_f32_32x32x16_bf16 v[96:111], v[2:5], v[128:131], v[96:111]
	ds_read_b128 v[2:5], v0
	v_add_u32_e32 v0, s40, v170
	v_mfma_f32_32x32x16_bf16 v[96:111], v[6:9], v[132:135], v[96:111]
	ds_read_b128 v[6:9], v0
	s_waitcnt lgkmcnt(0)
	v_mfma_f32_32x32x16_bf16 v[96:111], v[2:5], v[136:139], v[96:111]
	v_mfma_f32_32x32x16_bf16 v[96:111], v[6:9], v[140:143], v[96:111]
	s_setprio 0
; #define LAS __attribute__((address_space(3)))
; DI float xh_max(float x) { const unsigned u = __float_as_uint(x); const auto r = __builtin_amdgcn_permlane32_swap(u, u, false, false); return fmaxf(__uint_as_float(r[0]), __uint_as_float(r[1])); }
; DI float xh_sum(float x) { const unsigned u = __float_as_uint(x); const auto r = __builtin_amdgcn_permlane32_swap(u, u, false, false); return __uint_as_float(r[0]) + __uint_as_float(r[1]); }
; template <int MODE>
; DI void co_finish(f32x16 S, LAS unsigned char* st, int key_base, AttnState& as, int tq, bool rowsel, int vb_in, int hh) {
;     const int vb = vb_in;
;     {
;         const int base = key_base + 4 * hh;
;         const int hi = (MODE == 0) ? (((tq - 31) >> 4) - base) : (tq - base);
;         const int lo = hi - 512;
; #pragma unroll
;         for (int i = 0; i < 16; ++i) { const int c = (i & 3) + 8 * (i >> 2); bool ok = (c <= hi); if (MODE == 2) ok = ok && (c > lo); if (MODE == 1) ok = ok && rowsel; S[i] = ok ? S[i] : -1e30f; }
;     }
;     float mx = S[0];
; #pragma unroll
;     for (int i = 1; i < 16; ++i) mx = fmaxf(mx, S[i]);
;     mx = xh_max(mx);
;     const float mxs = mx * SM_SCALE; const bool need = mxs > as.m + 8.f;
;     const float mnew = need ? mxs : as.m, muse = -fmaxf(mnew, -1e20f); float ps = 0.f;
; #pragma unroll
;     for (int i = 0; i < 16; ++i) { const float p = __builtin_amdgcn_exp2f(__builtin_fmaf(S[i], SM_SCALE, muse)); S[i] = p; ps += p; }
;     ps = xh_sum(ps);
;     if (__builtin_amdgcn_ballot_w64(need) != 0ull) {
;         const float alpha = __builtin_amdgcn_exp2f(as.m - mnew);
;         as.l *= alpha;
; #pragma unroll
;         for (int dt = 0; dt < 4; ++dt)
; #pragma unroll
;             for (int i = 0; i < 16; ++i) as.acc[dt][i] *= alpha;
;     }
.LBB0_548:
	s_andn2_b64 vcc, exec, s[36:37]
	s_cbranch_vccnz .LBB0_552
	s_add_i32 s88, s59, s74
	s_cmp_ge_i32 s88, 31
	s_cbranch_scc1 .Lfastf_sel
	v_add_u32_e32 v0, s74, v145
	v_cmp_lt_i32_e32 vcc, -1, v0
	s_and_b64 vcc, s[26:27], vcc
	s_nop 0
	v_cndmask_b32_e32 v2, v153, v16, vcc
	v_cmp_lt_i32_e32 vcc, 0, v0
	s_and_b64 vcc, s[26:27], vcc
	v_max_f32_e32 v174, v2, v2
	v_cndmask_b32_e32 v3, v153, v17, vcc
	v_cmp_lt_i32_e32 vcc, 1, v0
	s_and_b64 vcc, s[26:27], vcc
	s_nop 0
	v_cndmask_b32_e32 v4, v153, v18, vcc
	v_cmp_lt_i32_e32 vcc, 2, v0
	s_and_b64 vcc, s[26:27], vcc
	s_nop 0
	v_cndmask_b32_e32 v5, v153, v19, vcc
	v_cmp_lt_i32_e32 vcc, 7, v0
	s_and_b64 vcc, s[26:27], vcc
	s_nop 0
	v_cndmask_b32_e32 v6, v153, v20, vcc
	v_cmp_lt_i32_e32 vcc, 8, v0
	s_and_b64 vcc, s[26:27], vcc
	s_nop 0
	v_cndmask_b32_e32 v7, v153, v21, vcc
	v_cmp_lt_i32_e32 vcc, 9, v0
	s_and_b64 vcc, s[26:27], vcc
	s_nop 0
	v_cndmask_b32_e32 v8, v153, v22, vcc
	v_cmp_lt_i32_e32 vcc, 10, v0
	s_and_b64 vcc, s[26:27], vcc
	s_nop 0
	v_cndmask_b32_e32 v9, v153, v23, vcc
	v_cmp_lt_i32_e32 vcc, 15, v0
	s_and_b64 vcc, s[26:27], vcc
	s_nop 0
	v_cndmask_b32_e32 v10, v153, v24, vcc
	v_cmp_lt_i32_e32 vcc, 16, v0
	s_and_b64 vcc, s[26:27], vcc
	s_nop 0
	v_cndmask_b32_e32 v11, v153, v25, vcc
	v_cmp_lt_i32_e32 vcc, 17, v0
	s_and_b64 vcc, s[26:27], vcc
	s_nop 0
	v_cndmask_b32_e32 v12, v153, v26, vcc
	v_cmp_lt_i32_e32 vcc, 18, v0
	s_and_b64 vcc, s[26:27], vcc
	s_nop 0
	v_cndmask_b32_e32 v13, v153, v27, vcc
	v_cmp_lt_i32_e32 vcc, 23, v0
	s_and_b64 vcc, s[26:27], vcc
	s_nop 0
	v_cndmask_b32_e32 v14, v153, v28, vcc
	v_cmp_lt_i32_e32 vcc, 24, v0
	s_and_b64 vcc, s[26:27], vcc
	s_nop 0
	v_cndmask_b32_e32 v15, v153, v29, vcc
	v_cmp_lt_i32_e32 vcc, 25, v0
	s_and_b64 vcc, s[26:27], vcc
	s_nop 0
	v_cndmask_b32_e32 v176, v153, v30, vcc
	v_cmp_lt_i32_e32 vcc, 26, v0
	v_max_f32_e32 v0, v3, v3
	v_max_f32_e32 v0, v174, v0
	v_max3_f32 v0, v0, v4, v5
	v_max3_f32 v0, v0, v6, v7
	v_max3_f32 v0, v0, v8, v9
	v_max3_f32 v0, v0, v10, v11
	s_and_b64 vcc, s[26:27], vcc
	v_max3_f32 v0, v0, v12, v13
	v_cndmask_b32_e32 v177, v153, v31, vcc
	v_max3_f32 v0, v0, v14, v15
	v_max3_f32 v0, v0, v176, v177
	v_mov_b32_e32 v174, v0
	s_nop 1
	v_permlane32_swap_b32_e32 v0, v174
	v_max_f32_e32 v174, v174, v174
	v_max_f32_e32 v0, v0, v0
	v_max_f32_e32 v0, v0, v174
	v_mul_f32_e32 v0, 0x3e0293ee, v0
	v_add_f32_e32 v174, 0x41000000, v175
	v_cmp_gt_f32_e32 vcc, v0, v174
	s_nop 1
	v_cndmask_b32_e32 v174, v175, v0, vcc
	v_max_f32_e32 v0, v174, v174
	v_max_f32_e32 v178, 0xe0ad78ec, v0
	v_fma_f32 v0, v2, s52, -v178
	v_exp_f32_e32 v0, v0
	v_fma_f32 v2, v3, s52, -v178
	v_exp_f32_e32 v2, v2
	v_fma_f32 v3, v4, s52, -v178
	v_exp_f32_e32 v3, v3
	v_fma_f32 v4, v5, s52, -v178
	v_exp_f32_e32 v4, v4
	v_add_f32_e32 v5, 0, v0
	v_add_f32_e32 v5, v2, v5
	v_add_f32_e32 v5, v3, v5
	v_add_f32_e32 v179, v4, v5
	v_fma_f32 v5, v6, s52, -v178
	v_exp_f32_e32 v5, v5
	v_fma_f32 v6, v7, s52, -v178
	v_exp_f32_e32 v6, v6
	v_fma_f32 v7, v8, s52, -v178
	v_exp_f32_e32 v7, v7
	v_fma_f32 v8, v9, s52, -v178
	v_exp_f32_e32 v8, v8
	v_add_f32_e32 v9, v5, v179
	v_add_f32_e32 v9, v6, v9
	v_add_f32_e32 v9, v7, v9
	v_add_f32_e32 v179, v8, v9
	v_fma_f32 v9, v10, s52, -v178
	v_exp_f32_e32 v9, v9
	v_fma_f32 v10, v11, s52, -v178
	v_exp_f32_e32 v10, v10
	v_fma_f32 v11, v12, s52, -v178
	v_exp_f32_e32 v11, v11
	v_fma_f32 v12, v13, s52, -v178
	v_exp_f32_e32 v12, v12
	v_add_f32_e32 v13, v9, v179
	v_add_f32_e32 v13, v10, v13
	v_add_f32_e32 v13, v11, v13
	v_add_f32_e32 v179, v12, v13
	v_fma_f32 v13, v14, s52, -v178
	v_exp_f32_e32 v13, v13
	v_fma_f32 v14, v15, s52, -v178
	v_exp_f32_e32 v14, v14
	v_fma_f32 v15, v176, s52, -v178
	v_exp_f32_e32 v15, v15
	v_fma_f32 v176, v177, s52, -v178
	v_exp_f32_e32 v176, v176
	v_add_f32_e32 v177, v13, v179
	v_add_f32_e32 v177, v14, v177
	v_add_f32_e32 v177, v15, v177
	v_add_f32_e32 v177, v176, v177
	v_mov_b32_e32 v178, v177
	s_nop 1
	v_permlane32_swap_b32_e32 v177, v178
	s_cbranch_vccz .LBB0_551
	v_sub_f32_e32 v175, v175, v174
	v_exp_f32_e32 v180, v175
	s_nop 0
	v_mul_f32_e32 v163, v163, v180
	v_pk_mul_f32 v[94:95], v[94:95], v[180:181] op_sel_hi:[1,0]
	v_pk_mul_f32 v[92:93], v[92:93], v[180:181] op_sel_hi:[1,0]
	v_pk_mul_f32 v[90:91], v[90:91], v[180:181] op_sel_hi:[1,0]
	v_pk_mul_f32 v[88:89], v[88:89], v[180:181] op_sel_hi:[1,0]
	v_pk_mul_f32 v[86:87], v[86:87], v[180:181] op_sel_hi:[1,0]
	v_pk_mul_f32 v[84:85], v[84:85], v[180:181] op_sel_hi:[1,0]
	v_pk_mul_f32 v[82:83], v[82:83], v[180:181] op_sel_hi:[1,0]
	v_pk_mul_f32 v[80:81], v[80:81], v[180:181] op_sel_hi:[1,0]
	v_pk_mul_f32 v[78:79], v[78:79], v[180:181] op_sel_hi:[1,0]
	v_pk_mul_f32 v[76:77], v[76:77], v[180:181] op_sel_hi:[1,0]
	v_pk_mul_f32 v[74:75], v[74:75], v[180:181] op_sel_hi:[1,0]
	v_pk_mul_f32 v[72:73], v[72:73], v[180:181] op_sel_hi:[1,0]
	v_pk_mul_f32 v[70:71], v[70:71], v[180:181] op_sel_hi:[1,0]
	v_pk_mul_f32 v[68:69], v[68:69], v[180:181] op_sel_hi:[1,0]
	v_pk_mul_f32 v[66:67], v[66:67], v[180:181] op_sel_hi:[1,0]
	v_pk_mul_f32 v[64:65], v[64:65], v[180:181] op_sel_hi:[1,0]
	v_pk_mul_f32 v[62:63], v[62:63], v[180:181] op_sel_hi:[1,0]
	v_pk_mul_f32 v[60:61], v[60:61], v[180:181] op_sel_hi:[1,0]
	v_pk_mul_f32 v[58:59], v[58:59], v[180:181] op_sel_hi:[1,0]
	v_pk_mul_f32 v[56:57], v[56:57], v[180:181] op_sel_hi:[1,0]
	v_pk_mul_f32 v[54:55], v[54:55], v[180:181] op_sel_hi:[1,0]
	v_pk_mul_f32 v[52:53], v[52:53], v[180:181] op_sel_hi:[1,0]
	v_pk_mul_f32 v[50:51], v[50:51], v[180:181] op_sel_hi:[1,0]
	v_pk_mul_f32 v[48:49], v[48:49], v[180:181] op_sel_hi:[1,0]
	v_pk_mul_f32 v[46:47], v[46:47], v[180:181] op_sel_hi:[1,0]
	v_pk_mul_f32 v[44:45], v[44:45], v[180:181] op_sel_hi:[1,0]
	v_pk_mul_f32 v[42:43], v[42:43], v[180:181] op_sel_hi:[1,0]
	v_pk_mul_f32 v[40:41], v[40:41], v[180:181] op_sel_hi:[1,0]
	v_pk_mul_f32 v[38:39], v[38:39], v[180:181] op_sel_hi:[1,0]
	v_pk_mul_f32 v[36:37], v[36:37], v[180:181] op_sel_hi:[1,0]
	v_pk_mul_f32 v[34:35], v[34:35], v[180:181] op_sel_hi:[1,0]
	v_pk_mul_f32 v[32:33], v[32:33], v[180:181] op_sel_hi:[1,0]

; #define CO_STEP2(list, n, i) do { \
;     if ((n) - 1 - (i) >= 1) asm volatile("s_waitcnt vmcnt(2)" ::: "memory"); else asm volatile("s_waitcnt vmcnt(0)" ::: "memory"); \
;     asm volatile("s_waitcnt lgkmcnt(0)" ::: "memory"); __builtin_amdgcn_s_barrier(); asm volatile("" ::: "memory"); \
;     if ((i) + 2 < (n)) co_issue(P, ring, ((i) + 2) & 3, (list)[(i) + 2], b, g, wave, lane); } while (0)
; #define CO_PIPE(MODE, REL, KB, RS) do { const bool rel_ = (REL); LAS unsigned char* sp_ = ring + (i & 3) * 16384; f32x16 Sn_; \
;     if (rel_) Sn_ = co_qk1(sp_, qf, ka); \
;     if (pend) co_finish<MODE>(Sp, pst, pkb, st, tq, prs, vb, hh); \
;     pend = rel_; if (rel_) { Sp = Sn_; pst = sp_; pkb = (KB); prs = (RS); } } while (0)
; DI void nsa_block_item(const Params& P, unsigned char* smem_g, int b, int g, int tb, int tid_in) {
;     ...
;     for (i = 0; i < n2; ++i) {
;         CO_STEP2(list2, n2, i); const int kb_ = (int)(list2[i] & 0xffffu); const int j = kb_ >> 6;
;         CO_PIPE(1, ((Uw >> j) & 1u) && kb_ <= t0 + 3, kb_, (bool)((mysel >> j) & 1u));
;     }
.LBB0_556:
	s_sub_i32 s74, 0, s16
	s_addk_i32 s72, 0x4000
	s_add_i32 s71, s71, 4
	v_mov_b32_e32 v239, s71
	ds_read_b32 v238, v239 offset:8
	ds_read_b32 v237, v239
	s_add_i32 s41, s73, -1
	s_cmp_lg_u32 s41, s33
	s_cbranch_scc0 .LBB0_558
	s_mov_b64 s[36:37], s[8:9]
	s_mov_b32 s64, s16
	s_mov_b32 s62, s40
	v_mov_b32_e32 v175, v174
	s_cmp_ge_i32 s41, s67
	s_mov_b64 s[2:3], -1
	s_cbranch_scc1 .LBB0_538
	s_branch .LBB0_539

; #define LAS __attribute__((address_space(3)))
; DI f32x16 co_qk1(LAS unsigned char* st, const bf16x8 (&qf)[8], int ka_in) {
;     const int ka = ka_in;
;     f32x16 S;
; #pragma unroll
;     for (int i = 0; i < 16; ++i) S[i] = 0.f;
;     __builtin_amdgcn_s_setprio(1);
; #pragma unroll
;     for (int ks = 0; ks < 8; ++ks) { const bf16x8 a = *(const LAS bf16x8*)(st + (ka ^ (32 * ks))); S = MFMA32(a, qf[ks], S); }
;     __builtin_amdgcn_s_setprio(0);
;     return S;
; }
; template <int MODE>
; DI void co_finish(f32x16 S, LAS unsigned char* st, int key_base, AttnState& as, int tq, bool rowsel, int vb_in, int hh) {
;     const int vb = vb_in;
;     {
;         const int base = key_base + 4 * hh;
;         const int hi = (MODE == 0) ? (((tq - 31) >> 4) - base) : (tq - base);
;         const int lo = hi - 512;
; #pragma unroll
;         for (int i = 0; i < 16; ++i) { const int c = (i & 3) + 8 * (i >> 2); bool ok = (c <= hi); if (MODE == 2) ok = ok && (c > lo); if (MODE == 1) ok = ok && rowsel; S[i] = ok ? S[i] : -1e30f; }
;     }
;     float mx = S[0];
; #pragma unroll
;     for (int i = 1; i < 16; ++i) mx = fmaxf(mx, S[i]);
;     mx = xh_max(mx);
;     const float mxs = mx * SM_SCALE; const bool need = mxs > as.m + 8.f;
;     const float mnew = need ? mxs : as.m, muse = -fmaxf(mnew, -1e20f); float ps = 0.f;
; #pragma unroll
;     for (int i = 0; i < 16; ++i) { const float p = __builtin_amdgcn_exp2f(__builtin_fmaf(S[i], SM_SCALE, muse)); S[i] = p; ps += p; }
;     ps = xh_sum(ps);
;     if (__builtin_amdgcn_ballot_w64(need) != 0ull) {
;         const float alpha = __builtin_amdgcn_exp2f(as.m - mnew);
;         as.l *= alpha;
; #pragma unroll
;         for (int dt = 0; dt < 4; ++dt)
; #pragma unroll
;             for (int i = 0; i < 16; ++i) as.acc[dt][i] *= alpha;
;     }
;     as.l += ps; as.m = mnew;
;     const bf16x8 p0 = pack8(S, 0), p1 = pack8(S, 1);
;     __builtin_amdgcn_s_setprio(1);
; #pragma unroll
;     for (int dt = 0; dt < 4; ++dt) {
;         LAS unsigned char* vp = st + 2048 * dt;
;         const bf16x8 a0 = cat44(*(const LAS s16x4*)(vp + (vb ^ 0)), *(const LAS s16x4*)(vp + (vb ^ 16))), a1 = cat44(*(const LAS s16x4*)(vp + (vb ^ 32)), *(const LAS s16x4*)(vp + (vb ^ 48)));
;         as.acc[dt] = MFMA32(a0, p0, as.acc[dt]); as.acc[dt] = MFMA32(a1, p1, as.acc[dt]);
;     }
.Lfast_sel:
	v_add_u32_e32 v252, s40, v162
	ds_read_b128 v[216:219], v252
	v_add_u32_e32 v252, s40, v164
	ds_read_b128 v[220:223], v252
	v_add_u32_e32 v252, s40, v165
	ds_read_b128 v[224:227], v252
	v_add_u32_e32 v252, s40, v166
	ds_read_b128 v[228:231], v252
	v_add_u32_e32 v252, s40, v167
	ds_read_b128 v[232:235], v252
	v_add_u32_e32 v252, s40, v168
	ds_read_b128 v[240:243], v252
	v_add_u32_e32 v252, s40, v169
	ds_read_b128 v[244:247], v252
	v_add_u32_e32 v252, s40, v170
	ds_read_b128 v[248:251], v252
	v_max_f32_e32 v0, v16, v17
	v_max3_f32 v0, v0, v18, v19
	v_max3_f32 v0, v0, v20, v21
	v_max3_f32 v0, v0, v22, v23
	s_waitcnt lgkmcnt(7)
	v_mfma_f32_32x32x16_bf16 v[96:111], v[216:219], v[112:115], 0
	v_max3_f32 v0, v0, v24, v25
	v_max3_f32 v0, v0, v26, v27
	v_max3_f32 v0, v0, v28, v29
	v_max3_f32 v0, v0, v30, v31
	v_mov_b32_e32 v15, v0
	v_add_u32_e32 v253, s62, v156
	v_add_u32_e32 v254, s62, v171
	v_permlane32_swap_b32_e32 v0, v15
	ds_read_b64 v[180:181], v253 offset:8192
	ds_read_b64 v[182:183], v254 offset:8192
	ds_read_b64 v[184:185], v253 offset:10240
	ds_read_b64 v[186:187], v254 offset:10240
	ds_read_b64 v[188:189], v253 offset:12288
	ds_read_b64 v[190:191], v254 offset:12288
	ds_read_b64 v[192:193], v253 offset:14336
	ds_read_b64 v[194:195], v254 offset:14336
	v_max_f32_e32 v0, v0, v15
	s_waitcnt lgkmcnt(14)
	v_mfma_f32_32x32x16_bf16 v[96:111], v[220:223], v[116:119], v[96:111]
	v_cndmask_b32_e64 v0, v153, v0, s[26:27]
	v_mul_f32_e32 v0, 0x3e0293ee, v0
	v_add_f32_e32 v15, 0x41000000, v175
	v_cmp_gt_f32_e32 vcc, v0, v15
	v_add_u32_e32 v255, s62, v172
	v_add_u32_e32 v214, s62, v173
	v_cndmask_b32_e32 v174, v175, v0, vcc
	v_max_f32_e32 v14, 0xe0ad78ec, v174
	v_mov_b32_e32 v13, 0x7149f2ca
	v_cndmask_b32_e64 v14, v13, v14, s[26:27]
	s_waitcnt lgkmcnt(13)
	v_mfma_f32_32x32x16_bf16 v[96:111], v[224:227], v[120:123], v[96:111]
	s_cbranch_vccz .Lfast_sel_nr
	v_sub_f32_e32 v175, v175, v174
	v_exp_f32_e32 v12, v175
	s_nop 0
	v_mul_f32_e32 v163, v163, v12
	v_pk_mul_f32 v[94:95], v[94:95], v[12:13] op_sel_hi:[1,0]
	v_pk_mul_f32 v[92:93], v[92:93], v[12:13] op_sel_hi:[1,0]
	v_pk_mul_f32 v[90:91], v[90:91], v[12:13] op_sel_hi:[1,0]
	v_pk_mul_f32 v[88:89], v[88:89], v[12:13] op_sel_hi:[1,0]
	v_pk_mul_f32 v[86:87], v[86:87], v[12:13] op_sel_hi:[1,0]
	v_pk_mul_f32 v[84:85], v[84:85], v[12:13] op_sel_hi:[1,0]
	v_pk_mul_f32 v[82:83], v[82:83], v[12:13] op_sel_hi:[1,0]
	v_pk_mul_f32 v[80:81], v[80:81], v[12:13] op_sel_hi:[1,0]
	v_pk_mul_f32 v[78:79], v[78:79], v[12:13] op_sel_hi:[1,0]
	v_pk_mul_f32 v[76:77], v[76:77], v[12:13] op_sel_hi:[1,0]
	v_pk_mul_f32 v[74:75], v[74:75], v[12:13] op_sel_hi:[1,0]
	v_pk_mul_f32 v[72:73], v[72:73], v[12:13] op_sel_hi:[1,0]
	v_pk_mul_f32 v[70:71], v[70:71], v[12:13] op_sel_hi:[1,0]
	v_pk_mul_f32 v[68:69], v[68:69], v[12:13] op_sel_hi:[1,0]
	v_pk_mul_f32 v[66:67], v[66:67], v[12:13] op_sel_hi:[1,0]
	v_pk_mul_f32 v[64:65], v[64:65], v[12:13] op_sel_hi:[1,0]
	v_pk_mul_f32 v[62:63], v[62:63], v[12:13] op_sel_hi:[1,0]
	v_pk_mul_f32 v[60:61], v[60:61], v[12:13] op_sel_hi:[1,0]
	v_pk_mul_f32 v[58:59], v[58:59], v[12:13] op_sel_hi:[1,0]
	v_pk_mul_f32 v[56:57], v[56:57], v[12:13] op_sel_hi:[1,0]
	v_pk_mul_f32 v[54:55], v[54:55], v[12:13] op_sel_hi:[1,0]
	v_pk_mul_f32 v[52:53], v[52:53], v[12:13] op_sel_hi:[1,0]
	v_pk_mul_f32 v[50:51], v[50:51], v[12:13] op_sel_hi:[1,0]
	v_pk_mul_f32 v[48:49], v[48:49], v[12:13] op_sel_hi:[1,0]
	v_pk_mul_f32 v[46:47], v[46:47], v[12:13] op_sel_hi:[1,0]
	v_pk_mul_f32 v[44:45], v[44:45], v[12:13] op_sel_hi:[1,0]
	v_pk_mul_f32 v[42:43], v[42:43], v[12:13] op_sel_hi:[1,0]
	v_pk_mul_f32 v[40:41], v[40:41], v[12:13] op_sel_hi:[1,0]
	v_pk_mul_f32 v[38:39], v[38:39], v[12:13] op_sel_hi:[1,0]
	v_pk_mul_f32 v[36:37], v[36:37], v[12:13] op_sel_hi:[1,0]
	v_pk_mul_f32 v[34:35], v[34:35], v[12:13] op_sel_hi:[1,0]
	v_pk_mul_f32 v[32:33], v[32:33], v[12:13] op_sel_hi:[1,0]
.Lfast_sel_nr:
	v_fma_f32 v16, v16, s52, -v14
	v_exp_f32_e32 v16, v16
	v_fma_f32 v17, v17, s52, -v14
	v_exp_f32_e32 v17, v17
	v_add_f32_e32 v10, 0, v16
	v_add_f32_e32 v10, v17, v10
	s_waitcnt lgkmcnt(12)
	v_mfma_f32_32x32x16_bf16 v[96:111], v[228:231], v[124:127], v[96:111]
	v_fma_f32 v18, v18, s52, -v14
	v_exp_f32_e32 v18, v18
	v_fma_f32 v19, v19, s52, -v14
	v_exp_f32_e32 v19, v19
	v_add_f32_e32 v10, v18, v10
	v_add_f32_e32 v10, v19, v10
	s_waitcnt lgkmcnt(11)
	v_mfma_f32_32x32x16_bf16 v[96:111], v[232:235], v[128:131], v[96:111]
	v_fma_f32 v20, v20, s52, -v14
	v_exp_f32_e32 v20, v20
	v_fma_f32 v21, v21, s52, -v14
	v_exp_f32_e32 v21, v21
	v_add_f32_e32 v10, v20, v10
	v_add_f32_e32 v10, v21, v10
	s_waitcnt lgkmcnt(10)
	v_mfma_f32_32x32x16_bf16 v[96:111], v[240:243], v[132:135], v[96:111]
	v_fma_f32 v22, v22, s52, -v14
	v_exp_f32_e32 v22, v22
	v_fma_f32 v23, v23, s52, -v14
	v_exp_f32_e32 v23, v23
	v_add_f32_e32 v10, v22, v10
	v_add_f32_e32 v10, v23, v10
	v_cvt_pk_bf16_f32 v2, v16, v17
	v_cvt_pk_bf16_f32 v3, v18, v19
	v_cvt_pk_bf16_f32 v4, v20, v21
	v_cvt_pk_bf16_f32 v5, v22, v23
	s_waitcnt lgkmcnt(9)
	v_mfma_f32_32x32x16_bf16 v[96:111], v[244:247], v[136:139], v[96:111]
	s_waitcnt lgkmcnt(4)
	v_mfma_f32_32x32x16_bf16 v[64:79], v[184:187], v[2:5], v[64:79]
	v_fma_f32 v24, v24, s52, -v14
	v_exp_f32_e32 v24, v24
	v_fma_f32 v25, v25, s52, -v14
	v_exp_f32_e32 v25, v25
	v_add_f32_e32 v10, v24, v10
	v_add_f32_e32 v10, v25, v10
	v_mfma_f32_32x32x16_bf16 v[96:111], v[248:251], v[140:143], v[96:111]
	v_mfma_f32_32x32x16_bf16 v[80:95], v[180:183], v[2:5], v[80:95]
	ds_read_b64 v[198:199], v255 offset:8192
	ds_read_b64 v[200:201], v214 offset:8192
	ds_read_b64 v[202:203], v255 offset:10240
	ds_read_b64 v[204:205], v214 offset:10240
	ds_read_b64 v[206:207], v255 offset:12288
	ds_read_b64 v[208:209], v214 offset:12288
	ds_read_b64 v[210:211], v255 offset:14336
	ds_read_b64 v[212:213], v214 offset:14336
	v_fma_f32 v26, v26, s52, -v14
	v_exp_f32_e32 v26, v26
	v_fma_f32 v27, v27, s52, -v14
	v_exp_f32_e32 v27, v27
	v_add_f32_e32 v10, v26, v10
	v_add_f32_e32 v10, v27, v10
	s_waitcnt lgkmcnt(10)
; #define LAS __attribute__((address_space(3)))
; DI float xh_max(float x) { const unsigned u = __float_as_uint(x); const auto r = __builtin_amdgcn_permlane32_swap(u, u, false, false); return fmaxf(__uint_as_float(r[0]), __uint_as_float(r[1])); }
; DI float xh_sum(float x) { const unsigned u = __float_as_uint(x); const auto r = __builtin_amdgcn_permlane32_swap(u, u, false, false); return __uint_as_float(r[0]) + __uint_as_float(r[1]); }
; #define MFMA32(a, b, c) __builtin_amdgcn_mfma_f32_32x32x16_bf16((a), (b), (c), 0, 0, 0)
; DI bf16x8 cat44(s16x4 a, s16x4 b) { return __builtin_shufflevector(a, b, 0, 1, 2, 3, 4, 5, 6, 7); }
; template <int MODE>
; DI void co_finish(f32x16 S, LAS unsigned char* st, int key_base, AttnState& as, int tq, bool rowsel, int vb_in, int hh) {
;     ...
;     float mx = S[0];
; #pragma unroll
;     for (int i = 1; i < 16; ++i) mx = fmaxf(mx, S[i]);
;     mx = xh_max(mx);
;     const float mxs = mx * SM_SCALE; const bool need = mxs > as.m + 8.f;
;     const float mnew = need ? mxs : as.m, muse = -fmaxf(mnew, -1e20f); float ps = 0.f;
; #pragma unroll
;     for (int i = 0; i < 16; ++i) { const float p = __builtin_amdgcn_exp2f(__builtin_fmaf(S[i], SM_SCALE, muse)); S[i] = p; ps += p; }
;     ps = xh_sum(ps);
;     if (__builtin_amdgcn_ballot_w64(need) != 0ull) {
;         const float alpha = __builtin_amdgcn_exp2f(as.m - mnew);
;         as.l *= alpha;
; #pragma unroll
;         for (int dt = 0; dt < 4; ++dt)
; #pragma unroll
;             for (int i = 0; i < 16; ++i) as.acc[dt][i] *= alpha;
;     }
;     as.l += ps; as.m = mnew;
;     const bf16x8 p0 = pack8(S, 0), p1 = pack8(S, 1);
;     __builtin_amdgcn_s_setprio(1);
; #pragma unroll
;     for (int dt = 0; dt < 4; ++dt) {
;         LAS unsigned char* vp = st + 2048 * dt;
;         const bf16x8 a0 = cat44(*(const LAS s16x4*)(vp + (vb ^ 0)), *(const LAS s16x4*)(vp + (vb ^ 16))), a1 = cat44(*(const LAS s16x4*)(vp + (vb ^ 32)), *(const LAS s16x4*)(vp + (vb ^ 48)));
;         as.acc[dt] = MFMA32(a0, p0, as.acc[dt]); as.acc[dt] = MFMA32(a1, p1, as.acc[dt]);
;     }
	v_mfma_f32_32x32x16_bf16 v[48:63], v[188:191], v[2:5], v[48:63]
	v_fma_f32 v28, v28, s52, -v14
	v_exp_f32_e32 v28, v28
	v_fma_f32 v29, v29, s52, -v14
	v_exp_f32_e32 v29, v29
	v_add_f32_e32 v10, v28, v10
	v_add_f32_e32 v10, v29, v10
	s_waitcnt lgkmcnt(8)
	v_mfma_f32_32x32x16_bf16 v[32:47], v[192:195], v[2:5], v[32:47]
	v_fma_f32 v30, v30, s52, -v14
	v_exp_f32_e32 v30, v30
	v_fma_f32 v31, v31, s52, -v14
	v_exp_f32_e32 v31, v31
	v_add_f32_e32 v10, v30, v10
	v_add_f32_e32 v10, v31, v10
	v_mov_b32_e32 v11, v10
	v_cvt_pk_bf16_f32 v6, v24, v25
	v_cvt_pk_bf16_f32 v7, v26, v27
	v_cvt_pk_bf16_f32 v8, v28, v29
	v_cvt_pk_bf16_f32 v9, v30, v31
	v_permlane32_swap_b32_e32 v10, v11
	v_add_f32_e32 v10, v10, v11
	v_add_f32_e32 v163, v10, v163
	s_waitcnt lgkmcnt(4)
	v_mfma_f32_32x32x16_bf16 v[64:79], v[202:205], v[6:9], v[64:79]
	v_mfma_f32_32x32x16_bf16 v[80:95], v[198:201], v[6:9], v[80:95]
	s_waitcnt lgkmcnt(2)
	v_mfma_f32_32x32x16_bf16 v[48:63], v[206:209], v[6:9], v[48:63]
	s_waitcnt lgkmcnt(0)
	v_mfma_f32_32x32x16_bf16 v[32:47], v[210:213], v[6:9], v[32:47]
	s_branch .LBB0_553
.Lfast_win:
	v_add_u32_e32 v252, s16, v162
	ds_read_b128 v[216:219], v252
	v_add_u32_e32 v252, s16, v164
	ds_read_b128 v[220:223], v252
	v_add_u32_e32 v252, s16, v165
	ds_read_b128 v[224:227], v252
	v_add_u32_e32 v252, s16, v166
	ds_read_b128 v[228:231], v252
	v_add_u32_e32 v252, s16, v167
	ds_read_b128 v[232:235], v252
	v_add_u32_e32 v252, s16, v168
	ds_read_b128 v[240:243], v252
	v_add_u32_e32 v252, s16, v169
	ds_read_b128 v[244:247], v252
	v_add_u32_e32 v252, s16, v170
	ds_read_b128 v[248:251], v252
	v_max_f32_e32 v0, v16, v17
	v_max3_f32 v0, v0, v18, v19
	v_max3_f32 v0, v0, v20, v21
	v_max3_f32 v0, v0, v22, v23
	s_waitcnt lgkmcnt(7)
	v_mfma_f32_32x32x16_bf16 v[96:111], v[216:219], v[112:115], 0
	v_max3_f32 v0, v0, v24, v25
	v_max3_f32 v0, v0, v26, v27
	v_max3_f32 v0, v0, v28, v29
	v_max3_f32 v0, v0, v30, v31
	v_mov_b32_e32 v15, v0
	v_add_u32_e32 v253, s62, v156
	v_add_u32_e32 v254, s62, v171
	v_permlane32_swap_b32_e32 v0, v15
	ds_read_b64 v[180:181], v253 offset:8192
	ds_read_b64 v[182:183], v254 offset:8192
	ds_read_b64 v[184:185], v253 offset:10240
	ds_read_b64 v[186:187], v254 offset:10240
	ds_read_b64 v[188:189], v253 offset:12288
	ds_read_b64 v[190:191], v254 offset:12288
	ds_read_b64 v[192:193], v253 offset:14336
	ds_read_b64 v[194:195], v254 offset:14336
	v_max_f32_e32 v0, v0, v15
	s_waitcnt lgkmcnt(14)
	v_mfma_f32_32x32x16_bf16 v[96:111], v[220:223], v[116:119], v[96:111]
	v_mul_f32_e32 v0, 0x3e0293ee, v0
	v_add_f32_e32 v15, 0x41000000, v177
	v_cmp_gt_f32_e32 vcc, v0, v15
	v_add_u32_e32 v255, s62, v172
	v_add_u32_e32 v214, s62, v173
	v_cndmask_b32_e32 v176, v177, v0, vcc
	v_max_f32_e32 v14, 0xe0ad78ec, v176
	s_waitcnt lgkmcnt(13)
	v_mfma_f32_32x32x16_bf16 v[96:111], v[224:227], v[120:123], v[96:111]
	s_cbranch_vccz .Lfast_win_nr
	v_sub_f32_e32 v177, v177, v176
	v_exp_f32_e32 v12, v177
	s_nop 0
	v_mul_f32_e32 v175, v175, v12
	v_pk_mul_f32 v[94:95], v[94:95], v[12:13] op_sel_hi:[1,0]
	v_pk_mul_f32 v[92:93], v[92:93], v[12:13] op_sel_hi:[1,0]
	v_pk_mul_f32 v[90:91], v[90:91], v[12:13] op_sel_hi:[1,0]
	v_pk_mul_f32 v[88:89], v[88:89], v[12:13] op_sel_hi:[1,0]
	v_pk_mul_f32 v[86:87], v[86:87], v[12:13] op_sel_hi:[1,0]
	v_pk_mul_f32 v[84:85], v[84:85], v[12:13] op_sel_hi:[1,0]
	v_pk_mul_f32 v[82:83], v[82:83], v[12:13] op_sel_hi:[1,0]
	v_pk_mul_f32 v[80:81], v[80:81], v[12:13] op_sel_hi:[1,0]
	v_pk_mul_f32 v[78:79], v[78:79], v[12:13] op_sel_hi:[1,0]
	v_pk_mul_f32 v[76:77], v[76:77], v[12:13] op_sel_hi:[1,0]
	v_pk_mul_f32 v[74:75], v[74:75], v[12:13] op_sel_hi:[1,0]
	v_pk_mul_f32 v[72:73], v[72:73], v[12:13] op_sel_hi:[1,0]
	v_pk_mul_f32 v[70:71], v[70:71], v[12:13] op_sel_hi:[1,0]
	v_pk_mul_f32 v[68:69], v[68:69], v[12:13] op_sel_hi:[1,0]
	v_pk_mul_f32 v[66:67], v[66:67], v[12:13] op_sel_hi:[1,0]
	v_pk_mul_f32 v[64:65], v[64:65], v[12:13] op_sel_hi:[1,0]
	v_pk_mul_f32 v[62:63], v[62:63], v[12:13] op_sel_hi:[1,0]
	v_pk_mul_f32 v[60:61], v[60:61], v[12:13] op_sel_hi:[1,0]
	v_pk_mul_f32 v[58:59], v[58:59], v[12:13] op_sel_hi:[1,0]
	v_pk_mul_f32 v[56:57], v[56:57], v[12:13] op_sel_hi:[1,0]
	v_pk_mul_f32 v[54:55], v[54:55], v[12:13] op_sel_hi:[1,0]
	v_pk_mul_f32 v[52:53], v[52:53], v[12:13] op_sel_hi:[1,0]
	v_pk_mul_f32 v[50:51], v[50:51], v[12:13] op_sel_hi:[1,0]
	v_pk_mul_f32 v[48:49], v[48:49], v[12:13] op_sel_hi:[1,0]
	v_pk_mul_f32 v[46:47], v[46:47], v[12:13] op_sel_hi:[1,0]
	v_pk_mul_f32 v[44:45], v[44:45], v[12:13] op_sel_hi:[1,0]
	v_pk_mul_f32 v[42:43], v[42:43], v[12:13] op_sel_hi:[1,0]
	v_pk_mul_f32 v[40:41], v[40:41], v[12:13] op_sel_hi:[1,0]
	v_pk_mul_f32 v[38:39], v[38:39], v[12:13] op_sel_hi:[1,0]
	v_pk_mul_f32 v[36:37], v[36:37], v[12:13] op_sel_hi:[1,0]
	v_pk_mul_f32 v[34:35], v[34:35], v[12:13] op_sel_hi:[1,0]
	v_pk_mul_f32 v[32:33], v[32:33], v[12:13] op_sel_hi:[1,0]
; #define LAS __attribute__((address_space(3)))
; DI float xh_max(float x) { const unsigned u = __float_as_uint(x); const auto r = __builtin_amdgcn_permlane32_swap(u, u, false, false); return fmaxf(__uint_as_float(r[0]), __uint_as_float(r[1])); }
; DI float xh_sum(float x) { const unsigned u = __float_as_uint(x); const auto r = __builtin_amdgcn_permlane32_swap(u, u, false, false); return __uint_as_float(r[0]) + __uint_as_float(r[1]); }
; #define MFMA32(a, b, c) __builtin_amdgcn_mfma_f32_32x32x16_bf16((a), (b), (c), 0, 0, 0)
; DI bf16x8 cat44(s16x4 a, s16x4 b) { return __builtin_shufflevector(a, b, 0, 1, 2, 3, 4, 5, 6, 7); }
; template <int MODE>
; DI void co_finish(f32x16 S, LAS unsigned char* st, int key_base, AttnState& as, int tq, bool rowsel, int vb_in, int hh) {
;     ...
;     float mx = S[0];
; #pragma unroll
;     for (int i = 1; i < 16; ++i) mx = fmaxf(mx, S[i]);
;     mx = xh_max(mx);
;     const float mxs = mx * SM_SCALE; const bool need = mxs > as.m + 8.f;
;     const float mnew = need ? mxs : as.m, muse = -fmaxf(mnew, -1e20f); float ps = 0.f;
; #pragma unroll
;     for (int i = 0; i < 16; ++i) { const float p = __builtin_amdgcn_exp2f(__builtin_fmaf(S[i], SM_SCALE, muse)); S[i] = p; ps += p; }
;     ps = xh_sum(ps);
;     if (__builtin_amdgcn_ballot_w64(need) != 0ull) {
;         const float alpha = __builtin_amdgcn_exp2f(as.m - mnew);
;         as.l *= alpha;
; #pragma unroll
;         for (int dt = 0; dt < 4; ++dt)
; #pragma unroll
;             for (int i = 0; i < 16; ++i) as.acc[dt][i] *= alpha;
;     }
;     as.l += ps; as.m = mnew;
;     const bf16x8 p0 = pack8(S, 0), p1 = pack8(S, 1);
;     __builtin_amdgcn_s_setprio(1);
; #pragma unroll
;     for (int dt = 0; dt < 4; ++dt) {
;         LAS unsigned char* vp = st + 2048 * dt;
;         const bf16x8 a0 = cat44(*(const LAS s16x4*)(vp + (vb ^ 0)), *(const LAS s16x4*)(vp + (vb ^ 16))), a1 = cat44(*(const LAS s16x4*)(vp + (vb ^ 32)), *(const LAS s16x4*)(vp + (vb ^ 48)));
;         as.acc[dt] = MFMA32(a0, p0, as.acc[dt]); as.acc[dt] = MFMA32(a1, p1, as.acc[dt]);
;     }
.Lfast_win_nr:
	v_fma_f32 v16, v16, s52, -v14
	v_exp_f32_e32 v16, v16
	v_fma_f32 v17, v17, s52, -v14
	v_exp_f32_e32 v17, v17
	v_add_f32_e32 v10, 0, v16
	v_add_f32_e32 v10, v17, v10
	s_waitcnt lgkmcnt(12)
	v_mfma_f32_32x32x16_bf16 v[96:111], v[228:231], v[124:127], v[96:111]
	v_fma_f32 v18, v18, s52, -v14
	v_exp_f32_e32 v18, v18
	v_fma_f32 v19, v19, s52, -v14
	v_exp_f32_e32 v19, v19
	v_add_f32_e32 v10, v18, v10
	v_add_f32_e32 v10, v19, v10
	s_waitcnt lgkmcnt(11)
	v_mfma_f32_32x32x16_bf16 v[96:111], v[232:235], v[128:131], v[96:111]
	v_fma_f32 v20, v20, s52, -v14
	v_exp_f32_e32 v20, v20
	v_fma_f32 v21, v21, s52, -v14
	v_exp_f32_e32 v21, v21
	v_add_f32_e32 v10, v20, v10
	v_add_f32_e32 v10, v21, v10
	s_waitcnt lgkmcnt(10)
	v_mfma_f32_32x32x16_bf16 v[96:111], v[240:243], v[132:135], v[96:111]
	v_fma_f32 v22, v22, s52, -v14
	v_exp_f32_e32 v22, v22
	v_fma_f32 v23, v23, s52, -v14
	v_exp_f32_e32 v23, v23
	v_add_f32_e32 v10, v22, v10
	v_add_f32_e32 v10, v23, v10
	v_cvt_pk_bf16_f32 v2, v16, v17
	v_cvt_pk_bf16_f32 v3, v18, v19
	v_cvt_pk_bf16_f32 v4, v20, v21
	v_cvt_pk_bf16_f32 v5, v22, v23
	s_waitcnt lgkmcnt(9)
	v_mfma_f32_32x32x16_bf16 v[96:111], v[244:247], v[136:139], v[96:111]
	s_waitcnt lgkmcnt(4)
	v_mfma_f32_32x32x16_bf16 v[64:79], v[184:187], v[2:5], v[64:79]
	v_fma_f32 v24, v24, s52, -v14
	v_exp_f32_e32 v24, v24
	v_fma_f32 v25, v25, s52, -v14
	v_exp_f32_e32 v25, v25
	v_add_f32_e32 v10, v24, v10
	v_add_f32_e32 v10, v25, v10
	v_mfma_f32_32x32x16_bf16 v[96:111], v[248:251], v[140:143], v[96:111]
	v_mfma_f32_32x32x16_bf16 v[80:95], v[180:183], v[2:5], v[80:95]
	ds_read_b64 v[198:199], v255 offset:8192
	ds_read_b64 v[200:201], v214 offset:8192
	ds_read_b64 v[202:203], v255 offset:10240
	ds_read_b64 v[204:205], v214 offset:10240
	ds_read_b64 v[206:207], v255 offset:12288
	ds_read_b64 v[208:209], v214 offset:12288
	ds_read_b64 v[210:211], v255 offset:14336
	ds_read_b64 v[212:213], v214 offset:14336
	v_fma_f32 v26, v26, s52, -v14
	v_exp_f32_e32 v26, v26
	v_fma_f32 v27, v27, s52, -v14
	v_exp_f32_e32 v27, v27
	v_add_f32_e32 v10, v26, v10
	v_add_f32_e32 v10, v27, v10
	s_waitcnt lgkmcnt(10)
	v_mfma_f32_32x32x16_bf16 v[48:63], v[188:191], v[2:5], v[48:63]
	v_fma_f32 v28, v28, s52, -v14
	v_exp_f32_e32 v28, v28
	v_fma_f32 v29, v29, s52, -v14
	v_exp_f32_e32 v29, v29
	v_add_f32_e32 v10, v28, v10
	v_add_f32_e32 v10, v29, v10
	s_waitcnt lgkmcnt(8)
	v_mfma_f32_32x32x16_bf16 v[32:47], v[192:195], v[2:5], v[32:47]
	v_fma_f32 v30, v30, s52, -v14
	v_exp_f32_e32 v30, v30
	v_fma_f32 v31, v31, s52, -v14
	v_exp_f32_e32 v31, v31
	v_add_f32_e32 v10, v30, v10
	v_add_f32_e32 v10, v31, v10
	v_mov_b32_e32 v11, v10
	v_cvt_pk_bf16_f32 v6, v24, v25
	v_cvt_pk_bf16_f32 v7, v26, v27
	v_cvt_pk_bf16_f32 v8, v28, v29
	v_cvt_pk_bf16_f32 v9, v30, v31
	v_permlane32_swap_b32_e32 v10, v11
	v_add_f32_e32 v10, v10, v11
	v_add_f32_e32 v175, v10, v175
	s_waitcnt lgkmcnt(4)
	v_mfma_f32_32x32x16_bf16 v[64:79], v[202:205], v[6:9], v[64:79]
	v_mfma_f32_32x32x16_bf16 v[80:95], v[198:201], v[6:9], v[80:95]
	s_waitcnt lgkmcnt(2)
	v_mfma_f32_32x32x16_bf16 v[48:63], v[206:209], v[6:9], v[48:63]
	s_waitcnt lgkmcnt(0)
	v_mfma_f32_32x32x16_bf16 v[32:47], v[210:213], v[6:9], v[32:47]
	s_branch .LBB0_522
.Lfastf_sel:
	v_max_f32_e32 v0, v16, v17
	v_max3_f32 v0, v0, v18, v19
	v_max3_f32 v0, v0, v20, v21
	v_max3_f32 v0, v0, v22, v23
	v_max3_f32 v0, v0, v24, v25
	v_max3_f32 v0, v0, v26, v27
	v_max3_f32 v0, v0, v28, v29
	v_max3_f32 v0, v0, v30, v31
	v_mov_b32_e32 v15, v0
	v_add_u32_e32 v253, s62, v156
	v_add_u32_e32 v254, s62, v171
	v_permlane32_swap_b32_e32 v0, v15
	ds_read_b64 v[180:181], v253 offset:8192
	ds_read_b64 v[182:183], v254 offset:8192
	ds_read_b64 v[184:185], v253 offset:10240
	ds_read_b64 v[186:187], v254 offset:10240
	ds_read_b64 v[188:189], v253 offset:12288
	ds_read_b64 v[190:191], v254 offset:12288
	ds_read_b64 v[192:193], v253 offset:14336
	ds_read_b64 v[194:195], v254 offset:14336
	v_max_f32_e32 v0, v0, v15
	v_cndmask_b32_e64 v0, v153, v0, s[26:27]
	v_mul_f32_e32 v0, 0x3e0293ee, v0
	v_add_f32_e32 v15, 0x41000000, v175
	v_cmp_gt_f32_e32 vcc, v0, v15
	v_add_u32_e32 v255, s62, v172
	v_add_u32_e32 v214, s62, v173
	v_cndmask_b32_e32 v174, v175, v0, vcc
	v_max_f32_e32 v14, 0xe0ad78ec, v174
	v_mov_b32_e32 v13, 0x7149f2ca
	v_cndmask_b32_e64 v14, v13, v14, s[26:27]
	s_cbranch_vccz .Lfastf_sel_nr
	v_sub_f32_e32 v175, v175, v174
	v_exp_f32_e32 v12, v175
	s_nop 0
	v_mul_f32_e32 v163, v163, v12
	v_pk_mul_f32 v[94:95], v[94:95], v[12:13] op_sel_hi:[1,0]
	v_pk_mul_f32 v[92:93], v[92:93], v[12:13] op_sel_hi:[1,0]
	v_pk_mul_f32 v[90:91], v[90:91], v[12:13] op_sel_hi:[1,0]
	v_pk_mul_f32 v[88:89], v[88:89], v[12:13] op_sel_hi:[1,0]
	v_pk_mul_f32 v[86:87], v[86:87], v[12:13] op_sel_hi:[1,0]
	v_pk_mul_f32 v[84:85], v[84:85], v[12:13] op_sel_hi:[1,0]
	v_pk_mul_f32 v[82:83], v[82:83], v[12:13] op_sel_hi:[1,0]
	v_pk_mul_f32 v[80:81], v[80:81], v[12:13] op_sel_hi:[1,0]
	v_pk_mul_f32 v[78:79], v[78:79], v[12:13] op_sel_hi:[1,0]
	v_pk_mul_f32 v[76:77], v[76:77], v[12:13] op_sel_hi:[1,0]
	v_pk_mul_f32 v[74:75], v[74:75], v[12:13] op_sel_hi:[1,0]
	v_pk_mul_f32 v[72:73], v[72:73], v[12:13] op_sel_hi:[1,0]
	v_pk_mul_f32 v[70:71], v[70:71], v[12:13] op_sel_hi:[1,0]
	v_pk_mul_f32 v[68:69], v[68:69], v[12:13] op_sel_hi:[1,0]
	v_pk_mul_f32 v[66:67], v[66:67], v[12:13] op_sel_hi:[1,0]
	v_pk_mul_f32 v[64:65], v[64:65], v[12:13] op_sel_hi:[1,0]
	v_pk_mul_f32 v[62:63], v[62:63], v[12:13] op_sel_hi:[1,0]
	v_pk_mul_f32 v[60:61], v[60:61], v[12:13] op_sel_hi:[1,0]
	v_pk_mul_f32 v[58:59], v[58:59], v[12:13] op_sel_hi:[1,0]
	v_pk_mul_f32 v[56:57], v[56:57], v[12:13] op_sel_hi:[1,0]
	v_pk_mul_f32 v[54:55], v[54:55], v[12:13] op_sel_hi:[1,0]
	v_pk_mul_f32 v[52:53], v[52:53], v[12:13] op_sel_hi:[1,0]
	v_pk_mul_f32 v[50:51], v[50:51], v[12:13] op_sel_hi:[1,0]
	v_pk_mul_f32 v[48:49], v[48:49], v[12:13] op_sel_hi:[1,0]
	v_pk_mul_f32 v[46:47], v[46:47], v[12:13] op_sel_hi:[1,0]
	v_pk_mul_f32 v[44:45], v[44:45], v[12:13] op_sel_hi:[1,0]
	v_pk_mul_f32 v[42:43], v[42:43], v[12:13] op_sel_hi:[1,0]
	v_pk_mul_f32 v[40:41], v[40:41], v[12:13] op_sel_hi:[1,0]
	v_pk_mul_f32 v[38:39], v[38:39], v[12:13] op_sel_hi:[1,0]
	v_pk_mul_f32 v[36:37], v[36:37], v[12:13] op_sel_hi:[1,0]
	v_pk_mul_f32 v[34:35], v[34:35], v[12:13] op_sel_hi:[1,0]
	v_pk_mul_f32 v[32:33], v[32:33], v[12:13] op_sel_hi:[1,0]
; #define LAS __attribute__((address_space(3)))
; DI float xh_sum(float x) { const unsigned u = __float_as_uint(x); const auto r = __builtin_amdgcn_permlane32_swap(u, u, false, false); return __uint_as_float(r[0]) + __uint_as_float(r[1]); }
; #define MFMA32(a, b, c) __builtin_amdgcn_mfma_f32_32x32x16_bf16((a), (b), (c), 0, 0, 0)
; DI bf16x8 cat44(s16x4 a, s16x4 b) { return __builtin_shufflevector(a, b, 0, 1, 2, 3, 4, 5, 6, 7); }
; template <int MODE>
; DI void co_finish(f32x16 S, LAS unsigned char* st, int key_base, AttnState& as, int tq, bool rowsel, int vb_in, int hh) {
;     ...
;     const float mnew = need ? mxs : as.m, muse = -fmaxf(mnew, -1e20f); float ps = 0.f;
; #pragma unroll
;     for (int i = 0; i < 16; ++i) { const float p = __builtin_amdgcn_exp2f(__builtin_fmaf(S[i], SM_SCALE, muse)); S[i] = p; ps += p; }
;     ps = xh_sum(ps);
;     if (__builtin_amdgcn_ballot_w64(need) != 0ull) {
;         const float alpha = __builtin_amdgcn_exp2f(as.m - mnew);
;         as.l *= alpha;
; #pragma unroll
;         for (int dt = 0; dt < 4; ++dt)
; #pragma unroll
;             for (int i = 0; i < 16; ++i) as.acc[dt][i] *= alpha;
;     }
;     as.l += ps; as.m = mnew;
;     const bf16x8 p0 = pack8(S, 0), p1 = pack8(S, 1);
;     __builtin_amdgcn_s_setprio(1);
; #pragma unroll
;     for (int dt = 0; dt < 4; ++dt) {
;         LAS unsigned char* vp = st + 2048 * dt;
;         const bf16x8 a0 = cat44(*(const LAS s16x4*)(vp + (vb ^ 0)), *(const LAS s16x4*)(vp + (vb ^ 16))), a1 = cat44(*(const LAS s16x4*)(vp + (vb ^ 32)), *(const LAS s16x4*)(vp + (vb ^ 48)));
;         as.acc[dt] = MFMA32(a0, p0, as.acc[dt]); as.acc[dt] = MFMA32(a1, p1, as.acc[dt]);
;     }
.Lfastf_sel_nr:
	v_fma_f32 v16, v16, s52, -v14
	v_exp_f32_e32 v16, v16
	v_fma_f32 v17, v17, s52, -v14
	v_exp_f32_e32 v17, v17
	v_add_f32_e32 v10, 0, v16
	v_add_f32_e32 v10, v17, v10
	v_fma_f32 v18, v18, s52, -v14
	v_exp_f32_e32 v18, v18
	v_fma_f32 v19, v19, s52, -v14
	v_exp_f32_e32 v19, v19
	v_add_f32_e32 v10, v18, v10
	v_add_f32_e32 v10, v19, v10
	v_fma_f32 v20, v20, s52, -v14
	v_exp_f32_e32 v20, v20
	v_fma_f32 v21, v21, s52, -v14
	v_exp_f32_e32 v21, v21
	v_add_f32_e32 v10, v20, v10
	v_add_f32_e32 v10, v21, v10
	v_fma_f32 v22, v22, s52, -v14
	v_exp_f32_e32 v22, v22
	v_fma_f32 v23, v23, s52, -v14
	v_exp_f32_e32 v23, v23
	v_add_f32_e32 v10, v22, v10
	v_add_f32_e32 v10, v23, v10
	v_cvt_pk_bf16_f32 v2, v16, v17
	v_cvt_pk_bf16_f32 v3, v18, v19
	v_cvt_pk_bf16_f32 v4, v20, v21
	v_cvt_pk_bf16_f32 v5, v22, v23
	s_nop 1
	s_waitcnt lgkmcnt(4)
	v_mfma_f32_32x32x16_bf16 v[64:79], v[184:187], v[2:5], v[64:79]
	v_fma_f32 v24, v24, s52, -v14
	v_exp_f32_e32 v24, v24
	v_fma_f32 v25, v25, s52, -v14
	v_exp_f32_e32 v25, v25
	v_add_f32_e32 v10, v24, v10
	v_add_f32_e32 v10, v25, v10
	v_mfma_f32_32x32x16_bf16 v[80:95], v[180:183], v[2:5], v[80:95]
	ds_read_b64 v[198:199], v255 offset:8192
	ds_read_b64 v[200:201], v214 offset:8192
	ds_read_b64 v[202:203], v255 offset:10240
	ds_read_b64 v[204:205], v214 offset:10240
	ds_read_b64 v[206:207], v255 offset:12288
	ds_read_b64 v[208:209], v214 offset:12288
	ds_read_b64 v[210:211], v255 offset:14336
	ds_read_b64 v[212:213], v214 offset:14336
	v_fma_f32 v26, v26, s52, -v14
	v_exp_f32_e32 v26, v26
	v_fma_f32 v27, v27, s52, -v14
	v_exp_f32_e32 v27, v27
	v_add_f32_e32 v10, v26, v10
	v_add_f32_e32 v10, v27, v10
	s_waitcnt lgkmcnt(10)
	v_mfma_f32_32x32x16_bf16 v[48:63], v[188:191], v[2:5], v[48:63]
	v_fma_f32 v28, v28, s52, -v14
	v_exp_f32_e32 v28, v28
	v_fma_f32 v29, v29, s52, -v14
	v_exp_f32_e32 v29, v29
	v_add_f32_e32 v10, v28, v10
	v_add_f32_e32 v10, v29, v10
	s_waitcnt lgkmcnt(8)
	v_mfma_f32_32x32x16_bf16 v[32:47], v[192:195], v[2:5], v[32:47]
	v_fma_f32 v30, v30, s52, -v14
	v_exp_f32_e32 v30, v30
	v_fma_f32 v31, v31, s52, -v14
	v_exp_f32_e32 v31, v31
	v_add_f32_e32 v10, v30, v10
	v_add_f32_e32 v10, v31, v10
	v_mov_b32_e32 v11, v10
	v_cvt_pk_bf16_f32 v6, v24, v25
	v_cvt_pk_bf16_f32 v7, v26, v27
	v_cvt_pk_bf16_f32 v8, v28, v29
	v_cvt_pk_bf16_f32 v9, v30, v31
	v_permlane32_swap_b32_e32 v10, v11
	v_add_f32_e32 v10, v10, v11
	v_add_f32_e32 v163, v10, v163
	s_waitcnt lgkmcnt(4)
	v_mfma_f32_32x32x16_bf16 v[64:79], v[202:205], v[6:9], v[64:79]
	v_mfma_f32_32x32x16_bf16 v[80:95], v[198:201], v[6:9], v[80:95]
	s_waitcnt lgkmcnt(2)
	v_mfma_f32_32x32x16_bf16 v[48:63], v[206:209], v[6:9], v[48:63]
	s_waitcnt lgkmcnt(0)
	v_mfma_f32_32x32x16_bf16 v[32:47], v[210:213], v[6:9], v[32:47]
	s_branch .LBB0_553
; #define LAS __attribute__((address_space(3)))
; DI float xh_max(float x) { const unsigned u = __float_as_uint(x); const auto r = __builtin_amdgcn_permlane32_swap(u, u, false, false); return fmaxf(__uint_as_float(r[0]), __uint_as_float(r[1])); }
; DI float xh_sum(float x) { const unsigned u = __float_as_uint(x); const auto r = __builtin_amdgcn_permlane32_swap(u, u, false, false); return __uint_as_float(r[0]) + __uint_as_float(r[1]); }
; #define MFMA32(a, b, c) __builtin_amdgcn_mfma_f32_32x32x16_bf16((a), (b), (c), 0, 0, 0)
; DI bf16x8 cat44(s16x4 a, s16x4 b) { return __builtin_shufflevector(a, b, 0, 1, 2, 3, 4, 5, 6, 7); }
; template <int MODE>
; DI void co_finish(f32x16 S, LAS unsigned char* st, int key_base, AttnState& as, int tq, bool rowsel, int vb_in, int hh) {
;     ...
;     float mx = S[0];
; #pragma unroll
;     for (int i = 1; i < 16; ++i) mx = fmaxf(mx, S[i]);
;     mx = xh_max(mx);
;     const float mxs = mx * SM_SCALE; const bool need = mxs > as.m + 8.f;
;     const float mnew = need ? mxs : as.m, muse = -fmaxf(mnew, -1e20f); float ps = 0.f;
; #pragma unroll
;     for (int i = 0; i < 16; ++i) { const float p = __builtin_amdgcn_exp2f(__builtin_fmaf(S[i], SM_SCALE, muse)); S[i] = p; ps += p; }
;     ps = xh_sum(ps);
;     if (__builtin_amdgcn_ballot_w64(need) != 0ull) {
;         const float alpha = __builtin_amdgcn_exp2f(as.m - mnew);
;         as.l *= alpha;
; #pragma unroll
;         for (int dt = 0; dt < 4; ++dt)
; #pragma unroll
;             for (int i = 0; i < 16; ++i) as.acc[dt][i] *= alpha;
;     }
;     as.l += ps; as.m = mnew;
;     const bf16x8 p0 = pack8(S, 0), p1 = pack8(S, 1);
;     __builtin_amdgcn_s_setprio(1);
; #pragma unroll
;     for (int dt = 0; dt < 4; ++dt) {
;         LAS unsigned char* vp = st + 2048 * dt;
;         const bf16x8 a0 = cat44(*(const LAS s16x4*)(vp + (vb ^ 0)), *(const LAS s16x4*)(vp + (vb ^ 16))), a1 = cat44(*(const LAS s16x4*)(vp + (vb ^ 32)), *(const LAS s16x4*)(vp + (vb ^ 48)));
;         as.acc[dt] = MFMA32(a0, p0, as.acc[dt]); as.acc[dt] = MFMA32(a1, p1, as.acc[dt]);
;     }
.Lfastf_win:
	v_max_f32_e32 v0, v16, v17
	v_max3_f32 v0, v0, v18, v19
	v_max3_f32 v0, v0, v20, v21
	v_max3_f32 v0, v0, v22, v23
	v_max3_f32 v0, v0, v24, v25
	v_max3_f32 v0, v0, v26, v27
	v_max3_f32 v0, v0, v28, v29
	v_max3_f32 v0, v0, v30, v31
	v_mov_b32_e32 v15, v0
	v_add_u32_e32 v253, s62, v156
	v_add_u32_e32 v254, s62, v171
	v_permlane32_swap_b32_e32 v0, v15
	ds_read_b64 v[180:181], v253 offset:8192
	ds_read_b64 v[182:183], v254 offset:8192
	ds_read_b64 v[184:185], v253 offset:10240
	ds_read_b64 v[186:187], v254 offset:10240
	ds_read_b64 v[188:189], v253 offset:12288
	ds_read_b64 v[190:191], v254 offset:12288
	ds_read_b64 v[192:193], v253 offset:14336
	ds_read_b64 v[194:195], v254 offset:14336
	v_max_f32_e32 v0, v0, v15
	v_mul_f32_e32 v0, 0x3e0293ee, v0
	v_add_f32_e32 v15, 0x41000000, v177
	v_cmp_gt_f32_e32 vcc, v0, v15
	v_add_u32_e32 v255, s62, v172
	v_add_u32_e32 v214, s62, v173
	v_cndmask_b32_e32 v176, v177, v0, vcc
	v_max_f32_e32 v14, 0xe0ad78ec, v176
	s_cbranch_vccz .Lfastf_win_nr
	v_sub_f32_e32 v177, v177, v176
	v_exp_f32_e32 v12, v177
	s_nop 0
	v_mul_f32_e32 v175, v175, v12
	v_pk_mul_f32 v[94:95], v[94:95], v[12:13] op_sel_hi:[1,0]
	v_pk_mul_f32 v[92:93], v[92:93], v[12:13] op_sel_hi:[1,0]
	v_pk_mul_f32 v[90:91], v[90:91], v[12:13] op_sel_hi:[1,0]
	v_pk_mul_f32 v[88:89], v[88:89], v[12:13] op_sel_hi:[1,0]
	v_pk_mul_f32 v[86:87], v[86:87], v[12:13] op_sel_hi:[1,0]
	v_pk_mul_f32 v[84:85], v[84:85], v[12:13] op_sel_hi:[1,0]
	v_pk_mul_f32 v[82:83], v[82:83], v[12:13] op_sel_hi:[1,0]
	v_pk_mul_f32 v[80:81], v[80:81], v[12:13] op_sel_hi:[1,0]
	v_pk_mul_f32 v[78:79], v[78:79], v[12:13] op_sel_hi:[1,0]
	v_pk_mul_f32 v[76:77], v[76:77], v[12:13] op_sel_hi:[1,0]
	v_pk_mul_f32 v[74:75], v[74:75], v[12:13] op_sel_hi:[1,0]
	v_pk_mul_f32 v[72:73], v[72:73], v[12:13] op_sel_hi:[1,0]
	v_pk_mul_f32 v[70:71], v[70:71], v[12:13] op_sel_hi:[1,0]
	v_pk_mul_f32 v[68:69], v[68:69], v[12:13] op_sel_hi:[1,0]
	v_pk_mul_f32 v[66:67], v[66:67], v[12:13] op_sel_hi:[1,0]
	v_pk_mul_f32 v[64:65], v[64:65], v[12:13] op_sel_hi:[1,0]
	v_pk_mul_f32 v[62:63], v[62:63], v[12:13] op_sel_hi:[1,0]
	v_pk_mul_f32 v[60:61], v[60:61], v[12:13] op_sel_hi:[1,0]
	v_pk_mul_f32 v[58:59], v[58:59], v[12:13] op_sel_hi:[1,0]
	v_pk_mul_f32 v[56:57], v[56:57], v[12:13] op_sel_hi:[1,0]
	v_pk_mul_f32 v[54:55], v[54:55], v[12:13] op_sel_hi:[1,0]
	v_pk_mul_f32 v[52:53], v[52:53], v[12:13] op_sel_hi:[1,0]
	v_pk_mul_f32 v[50:51], v[50:51], v[12:13] op_sel_hi:[1,0]
	v_pk_mul_f32 v[48:49], v[48:49], v[12:13] op_sel_hi:[1,0]
	v_pk_mul_f32 v[46:47], v[46:47], v[12:13] op_sel_hi:[1,0]
	v_pk_mul_f32 v[44:45], v[44:45], v[12:13] op_sel_hi:[1,0]
	v_pk_mul_f32 v[42:43], v[42:43], v[12:13] op_sel_hi:[1,0]
	v_pk_mul_f32 v[40:41], v[40:41], v[12:13] op_sel_hi:[1,0]
	v_pk_mul_f32 v[38:39], v[38:39], v[12:13] op_sel_hi:[1,0]
	v_pk_mul_f32 v[36:37], v[36:37], v[12:13] op_sel_hi:[1,0]
	v_pk_mul_f32 v[34:35], v[34:35], v[12:13] op_sel_hi:[1,0]
	v_pk_mul_f32 v[32:33], v[32:33], v[12:13] op_sel_hi:[1,0]
.Lfastf_win_nr:
	v_fma_f32 v16, v16, s52, -v14
	v_exp_f32_e32 v16, v16
	v_fma_f32 v17, v17, s52, -v14
	v_exp_f32_e32 v17, v17
	v_add_f32_e32 v10, 0, v16
	v_add_f32_e32 v10, v17, v10
	v_fma_f32 v18, v18, s52, -v14
	v_exp_f32_e32 v18, v18
	v_fma_f32 v19, v19, s52, -v14
	v_exp_f32_e32 v19, v19
	v_add_f32_e32 v10, v18, v10
	v_add_f32_e32 v10, v19, v10
	v_fma_f32 v20, v20, s52, -v14
	v_exp_f32_e32 v20, v20
	v_fma_f32 v21, v21, s52, -v14
	v_exp_f32_e32 v21, v21
	v_add_f32_e32 v10, v20, v10
	v_add_f32_e32 v10, v21, v10
	v_fma_f32 v22, v22, s52, -v14
	v_exp_f32_e32 v22, v22
	v_fma_f32 v23, v23, s52, -v14
	v_exp_f32_e32 v23, v23
	v_add_f32_e32 v10, v22, v10
	v_add_f32_e32 v10, v23, v10
	v_cvt_pk_bf16_f32 v2, v16, v17
	v_cvt_pk_bf16_f32 v3, v18, v19
	v_cvt_pk_bf16_f32 v4, v20, v21
	v_cvt_pk_bf16_f32 v5, v22, v23
	s_nop 1
	s_waitcnt lgkmcnt(4)
	v_mfma_f32_32x32x16_bf16 v[64:79], v[184:187], v[2:5], v[64:79]
	v_fma_f32 v24, v24, s52, -v14
	v_exp_f32_e32 v24, v24
	v_fma_f32 v25, v25, s52, -v14
	v_exp_f32_e32 v25, v25
	v_add_f32_e32 v10, v24, v10
	v_add_f32_e32 v10, v25, v10
	v_mfma_f32_32x32x16_bf16 v[80:95], v[180:183], v[2:5], v[80:95]
	ds_read_b64 v[198:199], v255 offset:8192
	ds_read_b64 v[200:201], v214 offset:8192
	ds_read_b64 v[202:203], v255 offset:10240
	ds_read_b64 v[204:205], v214 offset:10240
	ds_read_b64 v[206:207], v255 offset:12288
	ds_read_b64 v[208:209], v214 offset:12288
	ds_read_b64 v[210:211], v255 offset:14336
	ds_read_b64 v[212:213], v214 offset:14336
	v_fma_f32 v26, v26, s52, -v14
	v_exp_f32_e32 v26, v26
	v_fma_f32 v27, v27, s52, -v14
	v_exp_f32_e32 v27, v27
	v_add_f32_e32 v10, v26, v10
	v_add_f32_e32 v10, v27, v10
	s_waitcnt lgkmcnt(10)
	v_mfma_f32_32x32x16_bf16 v[48:63], v[188:191], v[2:5], v[48:63]
	v_fma_f32 v28, v28, s52, -v14
	v_exp_f32_e32 v28, v28
	v_fma_f32 v29, v29, s52, -v14
	v_exp_f32_e32 v29, v29
	v_add_f32_e32 v10, v28, v10
	v_add_f32_e32 v10, v29, v10
	s_waitcnt lgkmcnt(8)
	v_mfma_f32_32x32x16_bf16 v[32:47], v[192:195], v[2:5], v[32:47]
	v_fma_f32 v30, v30, s52, -v14
	v_exp_f32_e32 v30, v30
	v_fma_f32 v31, v31, s52, -v14
	v_exp_f32_e32 v31, v31
	v_add_f32_e32 v10, v30, v10
	v_add_f32_e32 v10, v31, v10
	v_mov_b32_e32 v11, v10
	v_cvt_pk_bf16_f32 v6, v24, v25
	v_cvt_pk_bf16_f32 v7, v26, v27
	v_cvt_pk_bf16_f32 v8, v28, v29
	v_cvt_pk_bf16_f32 v9, v30, v31
	v_permlane32_swap_b32_e32 v10, v11
	v_add_f32_e32 v10, v10, v11
	v_add_f32_e32 v175, v10, v175
	s_waitcnt lgkmcnt(4)
	v_mfma_f32_32x32x16_bf16 v[64:79], v[202:205], v[6:9], v[64:79]
	v_mfma_f32_32x32x16_bf16 v[80:95], v[198:201], v[6:9], v[80:95]
	s_waitcnt lgkmcnt(2)
	v_mfma_f32_32x32x16_bf16 v[48:63], v[206:209], v[6:9], v[48:63]
	s_waitcnt lgkmcnt(0)
	v_mfma_f32_32x32x16_bf16 v[32:47], v[210:213], v[6:9], v[32:47]
	s_branch .LBB0_523
